# stack6 + first K-loop iteration of every EpiBf16 unit peeled with SrcC=0 (no accumulator zero-init)
# baseline (speedup 1.0000x reference)
.LBB0_333:
	s_add_u32 s16, s16, 0x80
	s_addc_u32 s17, s17, 0
	s_add_u32 s64, s20, 0x100
	s_addc_u32 s65, s21, 0
	s_mov_b32 s20, 0
	s_add_i32 s66, s20, 2
	s_add_u32 s67, s16, 0x80
	s_addc_u32 s21, s17, 0
	s_add_i32 s72, 0, 0x10000
	s_cmp_eq_u32 s58, s20
	s_cselect_b32 s21, s1, s21
	s_cselect_b32 s20, s0, s67
	v_add_u32_e32 v140, s72, v143
	s_cselect_b32 s71, s15, s65
	s_cselect_b32 s70, s14, s64
	s_add_i32 s67, 0, 0x14000
	ds_read_b128 v[160:163], v140
	ds_read_b128 v[164:167], v140 offset:1024
	ds_read_b128 v[168:171], v140 offset:2048
	ds_read_b128 v[172:175], v140 offset:3072
	v_add_u32_e32 v140, s67, v143
	ds_read_b128 v[176:179], v140
	ds_read_b128 v[180:183], v140 offset:1024
	ds_read_b128 v[184:187], v140 offset:2048
	ds_read_b128 v[188:191], v140 offset:3072
	v_lshl_add_u64 v[140:141], s[16:17], 0, v[136:137]
	s_add_i32 m0, s19, 0xc000
	ds_read_b128 v[192:195], v146
	ds_read_b128 v[196:199], v146 offset:1024
	ds_read_b128 v[200:203], v146 offset:2048
	ds_read_b128 v[204:207], v146 offset:3072
	ds_read_b128 v[208:211], v146 offset:4096
	ds_read_b128 v[212:215], v146 offset:5120
	ds_read_b128 v[216:219], v146 offset:6144
	ds_read_b128 v[220:223], v146 offset:7168
	global_load_lds_dwordx4 v[140:141], off
	v_lshl_add_u64 v[140:141], s[16:17], 0, v[138:139]
	s_add_i32 m0, s19, 0xe000
	s_nop 0
	global_load_lds_dwordx4 v[140:141], off
	s_waitcnt vmcnt(8)
	s_waitcnt lgkmcnt(0)
	s_barrier
	s_waitcnt lgkmcnt(0)
	v_mfma_f32_16x16x32_bf16 v[126:129], v[160:163], v[192:195], 0
	v_mfma_f32_16x16x32_bf16 v[122:125], v[168:171], v[192:195], 0
	v_mfma_f32_16x16x32_bf16 v[110:113], v[160:163], v[200:203], 0
	v_mfma_f32_16x16x32_bf16 v[106:109], v[168:171], v[200:203], 0
	v_mfma_f32_16x16x32_bf16 v[94:97], v[160:163], v[208:211], 0
	v_mfma_f32_16x16x32_bf16 v[90:93], v[168:171], v[208:211], 0
	v_mfma_f32_16x16x32_bf16 v[78:81], v[160:163], v[216:219], 0
	v_mfma_f32_16x16x32_bf16 v[74:77], v[168:171], v[216:219], 0
	v_mfma_f32_16x16x32_bf16 v[126:129], v[164:167], v[196:199], v[126:129]
	v_mfma_f32_16x16x32_bf16 v[122:125], v[172:175], v[196:199], v[122:125]
	v_mfma_f32_16x16x32_bf16 v[110:113], v[164:167], v[204:207], v[110:113]
	v_mfma_f32_16x16x32_bf16 v[106:109], v[172:175], v[204:207], v[106:109]
	v_mfma_f32_16x16x32_bf16 v[94:97], v[164:167], v[212:215], v[94:97]
	v_mfma_f32_16x16x32_bf16 v[90:93], v[172:175], v[212:215], v[90:93]
	v_mfma_f32_16x16x32_bf16 v[78:81], v[164:167], v[220:223], v[78:81]
	v_mfma_f32_16x16x32_bf16 v[74:77], v[172:175], v[220:223], v[74:77]
	v_mfma_f32_16x16x32_bf16 v[118:121], v[176:179], v[192:195], 0
	v_mfma_f32_16x16x32_bf16 v[114:117], v[184:187], v[192:195], 0
	v_mfma_f32_16x16x32_bf16 v[102:105], v[176:179], v[200:203], 0
	v_mfma_f32_16x16x32_bf16 v[98:101], v[184:187], v[200:203], 0
	v_mfma_f32_16x16x32_bf16 v[86:89], v[176:179], v[208:211], 0
	v_mfma_f32_16x16x32_bf16 v[82:85], v[184:187], v[208:211], 0
	v_mfma_f32_16x16x32_bf16 v[70:73], v[176:179], v[216:219], 0
	v_mfma_f32_16x16x32_bf16 v[66:69], v[184:187], v[216:219], 0
	v_mfma_f32_16x16x32_bf16 v[118:121], v[180:183], v[196:199], v[118:121]
	v_mfma_f32_16x16x32_bf16 v[114:117], v[188:191], v[196:199], v[114:117]
	v_mfma_f32_16x16x32_bf16 v[102:105], v[180:183], v[204:207], v[102:105]
	v_mfma_f32_16x16x32_bf16 v[98:101], v[188:191], v[204:207], v[98:101]
	v_mfma_f32_16x16x32_bf16 v[86:89], v[180:183], v[212:215], v[86:89]
	v_mfma_f32_16x16x32_bf16 v[82:85], v[188:191], v[212:215], v[82:85]
	v_mfma_f32_16x16x32_bf16 v[70:73], v[180:183], v[220:223], v[70:73]
	v_mfma_f32_16x16x32_bf16 v[66:69], v[188:191], v[220:223], v[66:69]
	s_barrier
	s_add_i32 s72, s72, s35
	v_lshl_add_u64 v[140:141], s[70:71], 0, v[0:1]
	s_mov_b32 m0, s72
	ds_read_b128 v[192:195], v146 offset:16384
	ds_read_b128 v[196:199], v146 offset:17408
	ds_read_b128 v[200:203], v146 offset:18432
	ds_read_b128 v[204:207], v146 offset:19456
	ds_read_b128 v[208:211], v146 offset:20480
	ds_read_b128 v[212:215], v146 offset:21504
	ds_read_b128 v[216:219], v146 offset:22528
	ds_read_b128 v[220:223], v146 offset:23552
	global_load_lds_dwordx4 v[140:141], off
	s_add_i32 m0, s72, 0x2000
	v_lshl_add_u64 v[148:149], s[70:71], 0, v[134:135]
	s_add_u32 s70, s70, s80
	s_addc_u32 s71, s71, 0
	s_add_i32 s67, s67, s35
	global_load_lds_dwordx4 v[148:149], off
	v_lshl_add_u64 v[224:225], s[70:71], 0, v[0:1]
	s_mov_b32 m0, s67
	v_lshl_add_u64 v[226:227], s[70:71], 0, v[134:135]
	global_load_lds_dwordx4 v[224:225], off
	s_add_i32 m0, s67, 0x2000
	v_lshl_add_u64 v[228:229], s[20:21], 0, v[130:131]
	global_load_lds_dwordx4 v[226:227], off
	s_mov_b32 m0, s19
	v_lshl_add_u64 v[230:231], s[20:21], 0, v[132:133]
	global_load_lds_dwordx4 v[228:229], off
	s_mov_b32 m0, s29
	s_nop 0
	global_load_lds_dwordx4 v[230:231], off
	s_waitcnt vmcnt(8)
	s_waitcnt lgkmcnt(0)
	s_barrier
	s_waitcnt lgkmcnt(0)
	v_mfma_f32_16x16x32_bf16 v[62:65], v[160:163], v[192:195], 0
	v_mfma_f32_16x16x32_bf16 v[58:61], v[168:171], v[192:195], 0
	v_mfma_f32_16x16x32_bf16 v[46:49], v[160:163], v[200:203], 0
	v_mfma_f32_16x16x32_bf16 v[42:45], v[168:171], v[200:203], 0
	v_mfma_f32_16x16x32_bf16 v[30:33], v[160:163], v[208:211], 0
	v_mfma_f32_16x16x32_bf16 v[26:29], v[168:171], v[208:211], 0
	v_mfma_f32_16x16x32_bf16 v[14:17], v[160:163], v[216:219], 0
	v_mfma_f32_16x16x32_bf16 v[10:13], v[168:171], v[216:219], 0
	v_mfma_f32_16x16x32_bf16 v[62:65], v[164:167], v[196:199], v[62:65]
	v_mfma_f32_16x16x32_bf16 v[58:61], v[172:175], v[196:199], v[58:61]
	v_mfma_f32_16x16x32_bf16 v[46:49], v[164:167], v[204:207], v[46:49]
	v_mfma_f32_16x16x32_bf16 v[42:45], v[172:175], v[204:207], v[42:45]
	v_mfma_f32_16x16x32_bf16 v[30:33], v[164:167], v[212:215], v[30:33]
	v_mfma_f32_16x16x32_bf16 v[26:29], v[172:175], v[212:215], v[26:29]
	v_mfma_f32_16x16x32_bf16 v[14:17], v[164:167], v[220:223], v[14:17]
	v_mfma_f32_16x16x32_bf16 v[10:13], v[172:175], v[220:223], v[10:13]
	v_mfma_f32_16x16x32_bf16 v[54:57], v[176:179], v[192:195], 0
	v_mfma_f32_16x16x32_bf16 v[50:53], v[184:187], v[192:195], 0
	v_mfma_f32_16x16x32_bf16 v[38:41], v[176:179], v[200:203], 0
	v_mfma_f32_16x16x32_bf16 v[34:37], v[184:187], v[200:203], 0
	v_mfma_f32_16x16x32_bf16 v[22:25], v[176:179], v[208:211], 0
	v_mfma_f32_16x16x32_bf16 v[18:21], v[184:187], v[208:211], 0
	v_mfma_f32_16x16x32_bf16 v[6:9], v[176:179], v[216:219], 0
	v_mfma_f32_16x16x32_bf16 v[2:5], v[184:187], v[216:219], 0
	v_mfma_f32_16x16x32_bf16 v[54:57], v[180:183], v[196:199], v[54:57]
	v_mfma_f32_16x16x32_bf16 v[50:53], v[188:191], v[196:199], v[50:53]
	v_mfma_f32_16x16x32_bf16 v[38:41], v[180:183], v[204:207], v[38:41]
	v_mfma_f32_16x16x32_bf16 v[34:37], v[188:191], v[204:207], v[34:37]
	v_mfma_f32_16x16x32_bf16 v[22:25], v[180:183], v[212:215], v[22:25]
	v_mfma_f32_16x16x32_bf16 v[18:21], v[188:191], v[212:215], v[18:21]
	v_mfma_f32_16x16x32_bf16 v[6:9], v[180:183], v[220:223], v[6:9]
	v_mfma_f32_16x16x32_bf16 v[2:5], v[188:191], v[220:223], v[2:5]
	s_barrier
	s_add_i32 s67, 0, 0x18000
	v_add_u32_e32 v159, s67, v143
	s_add_i32 s70, 0, 0x1c000
	ds_read_b128 v[160:163], v159
	ds_read_b128 v[164:167], v159 offset:1024
	ds_read_b128 v[168:171], v159 offset:2048
	ds_read_b128 v[172:175], v159 offset:3072
	v_add_u32_e32 v159, s70, v143
	ds_read_b128 v[176:179], v159
	ds_read_b128 v[180:183], v159 offset:1024
	ds_read_b128 v[184:187], v159 offset:2048
	ds_read_b128 v[188:191], v159 offset:3072
	s_add_u32 s20, s20, s80
	s_addc_u32 s21, s21, 0
	s_mov_b32 m0, s30
	v_lshl_add_u64 v[232:233], s[20:21], 0, v[130:131]
	ds_read_b128 v[192:195], v146 offset:32768
	ds_read_b128 v[196:199], v146 offset:33792
	ds_read_b128 v[200:203], v146 offset:34816
	ds_read_b128 v[204:207], v146 offset:35840
	ds_read_b128 v[208:211], v146 offset:36864
	ds_read_b128 v[212:215], v146 offset:37888
	ds_read_b128 v[216:219], v146 offset:38912
	ds_read_b128 v[220:223], v146 offset:39936
	global_load_lds_dwordx4 v[232:233], off
	v_lshl_add_u64 v[232:233], s[20:21], 0, v[132:133]
	s_mov_b32 m0, s31
	s_nop 0
	global_load_lds_dwordx4 v[232:233], off
	s_waitcnt vmcnt(8)
	s_waitcnt lgkmcnt(0)
	s_barrier
	s_waitcnt lgkmcnt(0)
	v_mfma_f32_16x16x32_bf16 v[126:129], v[160:163], v[192:195], v[126:129]
	v_mfma_f32_16x16x32_bf16 v[122:125], v[168:171], v[192:195], v[122:125]
	v_mfma_f32_16x16x32_bf16 v[110:113], v[160:163], v[200:203], v[110:113]
	v_mfma_f32_16x16x32_bf16 v[106:109], v[168:171], v[200:203], v[106:109]
	v_mfma_f32_16x16x32_bf16 v[94:97], v[160:163], v[208:211], v[94:97]
	v_mfma_f32_16x16x32_bf16 v[90:93], v[168:171], v[208:211], v[90:93]
	v_mfma_f32_16x16x32_bf16 v[78:81], v[160:163], v[216:219], v[78:81]
	v_mfma_f32_16x16x32_bf16 v[74:77], v[168:171], v[216:219], v[74:77]
	v_mfma_f32_16x16x32_bf16 v[126:129], v[164:167], v[196:199], v[126:129]
	v_mfma_f32_16x16x32_bf16 v[122:125], v[172:175], v[196:199], v[122:125]
	v_mfma_f32_16x16x32_bf16 v[110:113], v[164:167], v[204:207], v[110:113]
	v_mfma_f32_16x16x32_bf16 v[106:109], v[172:175], v[204:207], v[106:109]
	v_mfma_f32_16x16x32_bf16 v[94:97], v[164:167], v[212:215], v[94:97]
	v_mfma_f32_16x16x32_bf16 v[90:93], v[172:175], v[212:215], v[90:93]
	v_mfma_f32_16x16x32_bf16 v[78:81], v[164:167], v[220:223], v[78:81]
	v_mfma_f32_16x16x32_bf16 v[74:77], v[172:175], v[220:223], v[74:77]
	v_mfma_f32_16x16x32_bf16 v[118:121], v[176:179], v[192:195], v[118:121]
	v_mfma_f32_16x16x32_bf16 v[114:117], v[184:187], v[192:195], v[114:117]
	v_mfma_f32_16x16x32_bf16 v[102:105], v[176:179], v[200:203], v[102:105]
	v_mfma_f32_16x16x32_bf16 v[98:101], v[184:187], v[200:203], v[98:101]
	v_mfma_f32_16x16x32_bf16 v[86:89], v[176:179], v[208:211], v[86:89]
	v_mfma_f32_16x16x32_bf16 v[82:85], v[184:187], v[208:211], v[82:85]
	v_mfma_f32_16x16x32_bf16 v[70:73], v[176:179], v[216:219], v[70:73]
	v_mfma_f32_16x16x32_bf16 v[66:69], v[184:187], v[216:219], v[66:69]
	v_mfma_f32_16x16x32_bf16 v[118:121], v[180:183], v[196:199], v[118:121]
	v_mfma_f32_16x16x32_bf16 v[114:117], v[188:191], v[196:199], v[114:117]
	v_mfma_f32_16x16x32_bf16 v[102:105], v[180:183], v[204:207], v[102:105]
	v_mfma_f32_16x16x32_bf16 v[98:101], v[188:191], v[204:207], v[98:101]
	v_mfma_f32_16x16x32_bf16 v[86:89], v[180:183], v[212:215], v[86:89]
	v_mfma_f32_16x16x32_bf16 v[82:85], v[188:191], v[212:215], v[82:85]
	v_mfma_f32_16x16x32_bf16 v[70:73], v[180:183], v[220:223], v[70:73]
	v_mfma_f32_16x16x32_bf16 v[66:69], v[188:191], v[220:223], v[66:69]
	s_barrier
	s_add_i32 s20, s67, s35
	v_lshl_add_u64 v[140:141], v[140:141], 0, s[94:95]
	s_mov_b32 m0, s20
	ds_read_b128 v[192:195], v146 offset:49152
	ds_read_b128 v[196:199], v146 offset:50176
	ds_read_b128 v[200:203], v146 offset:51200
	ds_read_b128 v[204:207], v146 offset:52224
	ds_read_b128 v[208:211], v146 offset:53248
	ds_read_b128 v[212:215], v146 offset:54272
	ds_read_b128 v[216:219], v146 offset:55296
	ds_read_b128 v[220:223], v146 offset:56320
	global_load_lds_dwordx4 v[140:141], off
	v_lshl_add_u64 v[140:141], v[148:149], 0, s[94:95]
	s_add_i32 m0, s20, 0x2000
	s_add_i32 s20, s70, s35
	global_load_lds_dwordx4 v[140:141], off
	v_lshl_add_u64 v[140:141], v[224:225], 0, s[94:95]
	s_mov_b32 m0, s20
	s_nop 0
	global_load_lds_dwordx4 v[140:141], off
	v_lshl_add_u64 v[140:141], v[226:227], 0, s[94:95]
	s_add_i32 m0, s20, 0x2000
	s_nop 0
	global_load_lds_dwordx4 v[140:141], off
	v_lshl_add_u64 v[140:141], v[228:229], 0, s[94:95]
	s_mov_b32 m0, s56
	s_nop 0
	global_load_lds_dwordx4 v[140:141], off
	v_lshl_add_u64 v[140:141], v[230:231], 0, s[94:95]
	s_mov_b32 m0, s57
	s_nop 0
	global_load_lds_dwordx4 v[140:141], off
	s_waitcnt vmcnt(8)
	s_waitcnt lgkmcnt(0)
	s_barrier
	s_waitcnt lgkmcnt(0)
	v_mfma_f32_16x16x32_bf16 v[62:65], v[160:163], v[192:195], v[62:65]
	v_mfma_f32_16x16x32_bf16 v[58:61], v[168:171], v[192:195], v[58:61]
	v_mfma_f32_16x16x32_bf16 v[46:49], v[160:163], v[200:203], v[46:49]
	v_mfma_f32_16x16x32_bf16 v[42:45], v[168:171], v[200:203], v[42:45]
	v_mfma_f32_16x16x32_bf16 v[30:33], v[160:163], v[208:211], v[30:33]
	v_mfma_f32_16x16x32_bf16 v[26:29], v[168:171], v[208:211], v[26:29]
	v_mfma_f32_16x16x32_bf16 v[14:17], v[160:163], v[216:219], v[14:17]
	v_mfma_f32_16x16x32_bf16 v[10:13], v[168:171], v[216:219], v[10:13]
	v_mfma_f32_16x16x32_bf16 v[62:65], v[164:167], v[196:199], v[62:65]
	v_mfma_f32_16x16x32_bf16 v[58:61], v[172:175], v[196:199], v[58:61]
	v_mfma_f32_16x16x32_bf16 v[46:49], v[164:167], v[204:207], v[46:49]
	v_mfma_f32_16x16x32_bf16 v[42:45], v[172:175], v[204:207], v[42:45]
	v_mfma_f32_16x16x32_bf16 v[30:33], v[164:167], v[212:215], v[30:33]
	v_mfma_f32_16x16x32_bf16 v[26:29], v[172:175], v[212:215], v[26:29]
	v_mfma_f32_16x16x32_bf16 v[14:17], v[164:167], v[220:223], v[14:17]
	v_mfma_f32_16x16x32_bf16 v[10:13], v[172:175], v[220:223], v[10:13]
	v_mfma_f32_16x16x32_bf16 v[54:57], v[176:179], v[192:195], v[54:57]
	v_mfma_f32_16x16x32_bf16 v[50:53], v[184:187], v[192:195], v[50:53]
	v_mfma_f32_16x16x32_bf16 v[38:41], v[176:179], v[200:203], v[38:41]
	v_mfma_f32_16x16x32_bf16 v[34:37], v[184:187], v[200:203], v[34:37]
	v_mfma_f32_16x16x32_bf16 v[22:25], v[176:179], v[208:211], v[22:25]
	v_mfma_f32_16x16x32_bf16 v[18:21], v[184:187], v[208:211], v[18:21]
	v_mfma_f32_16x16x32_bf16 v[6:9], v[176:179], v[216:219], v[6:9]
	v_mfma_f32_16x16x32_bf16 v[2:5], v[184:187], v[216:219], v[2:5]
	v_mfma_f32_16x16x32_bf16 v[54:57], v[180:183], v[196:199], v[54:57]
	v_mfma_f32_16x16x32_bf16 v[50:53], v[188:191], v[196:199], v[50:53]
	v_mfma_f32_16x16x32_bf16 v[38:41], v[180:183], v[204:207], v[38:41]
	v_mfma_f32_16x16x32_bf16 v[34:37], v[188:191], v[204:207], v[34:37]
	v_mfma_f32_16x16x32_bf16 v[22:25], v[180:183], v[212:215], v[22:25]
	v_mfma_f32_16x16x32_bf16 v[18:21], v[188:191], v[212:215], v[18:21]
	v_mfma_f32_16x16x32_bf16 v[6:9], v[180:183], v[220:223], v[6:9]
	v_mfma_f32_16x16x32_bf16 v[2:5], v[188:191], v[220:223], v[2:5]
	s_barrier
	s_add_u32 s16, s16, 0x100
	s_addc_u32 s17, s17, 0
	s_add_u32 s64, s64, 0x100
	s_addc_u32 s65, s65, 0
	s_cmp_ge_u32 s66, s55
	s_mov_b32 s20, s66
	s_cbranch_scc0 .LBB0_334
	s_branch .Lkexit_334

.Lkexit_334:
	s_and_b64 vcc, exec, s[10:11]
	s_cbranch_vccz .LBB0_337
	s_barrier

.LBB0_359:
	s_add_u32 s2, s2, 0x80
	s_addc_u32 s3, s3, 0
	s_add_u32 s19, s10, 0x100
	s_addc_u32 s29, s11, 0
	s_mov_b32 s10, 0
	s_waitcnt lgkmcnt(0)
	s_add_i32 s30, s10, 2
	s_add_u32 s31, s2, 0x80
	s_addc_u32 s11, s3, 0
	s_add_i32 s35, 0, 0x10000
	s_cmp_eq_u32 s58, s10
	s_cselect_b32 s11, s1, s11
	s_cselect_b32 s10, s0, s31
	v_add_u32_e32 v148, s35, v160
	s_cselect_b32 s67, s7, s29
	s_cselect_b32 s66, s6, s19
	s_add_i32 s31, 0, 0x14000
	ds_read_b128 v[140:143], v148
	ds_read_b128 v[144:147], v148 offset:1024
	ds_read_b128 v[180:183], v148 offset:2048
	ds_read_b128 v[184:187], v148 offset:3072
	v_add_u32_e32 v148, s31, v160
	ds_read_b128 v[188:191], v148
	ds_read_b128 v[192:195], v148 offset:1024
	ds_read_b128 v[196:199], v148 offset:2048
	ds_read_b128 v[200:203], v148 offset:3072
	v_lshl_add_u64 v[148:149], s[2:3], 0, v[136:137]
	s_add_i32 m0, s23, 0xc000
	ds_read_b128 v[204:207], v172
	ds_read_b128 v[208:211], v172 offset:1024
	ds_read_b128 v[212:215], v172 offset:2048
	ds_read_b128 v[216:219], v172 offset:3072
	ds_read_b128 v[220:223], v172 offset:4096
	ds_read_b128 v[224:227], v172 offset:5120
	ds_read_b128 v[228:231], v172 offset:6144
	ds_read_b128 v[232:235], v172 offset:7168
	global_load_lds_dwordx4 v[148:149], off
	v_lshl_add_u64 v[148:149], s[2:3], 0, v[138:139]
	s_add_i32 m0, s23, 0xe000
	s_nop 0
	global_load_lds_dwordx4 v[148:149], off
	s_waitcnt vmcnt(8)
	s_waitcnt lgkmcnt(0)
	s_barrier
	s_waitcnt lgkmcnt(0)
	v_mfma_f32_16x16x32_bf16 v[126:129], v[140:143], v[204:207], 0
	v_mfma_f32_16x16x32_bf16 v[122:125], v[180:183], v[204:207], 0
	v_mfma_f32_16x16x32_bf16 v[110:113], v[140:143], v[212:215], 0
	v_mfma_f32_16x16x32_bf16 v[106:109], v[180:183], v[212:215], 0
	v_mfma_f32_16x16x32_bf16 v[94:97], v[140:143], v[220:223], 0
	v_mfma_f32_16x16x32_bf16 v[90:93], v[180:183], v[220:223], 0
	v_mfma_f32_16x16x32_bf16 v[78:81], v[140:143], v[228:231], 0
	v_mfma_f32_16x16x32_bf16 v[74:77], v[180:183], v[228:231], 0
	v_mfma_f32_16x16x32_bf16 v[126:129], v[144:147], v[208:211], v[126:129]
	v_mfma_f32_16x16x32_bf16 v[122:125], v[184:187], v[208:211], v[122:125]
	v_mfma_f32_16x16x32_bf16 v[110:113], v[144:147], v[216:219], v[110:113]
	v_mfma_f32_16x16x32_bf16 v[106:109], v[184:187], v[216:219], v[106:109]
	v_mfma_f32_16x16x32_bf16 v[94:97], v[144:147], v[224:227], v[94:97]
	v_mfma_f32_16x16x32_bf16 v[90:93], v[184:187], v[224:227], v[90:93]
	v_mfma_f32_16x16x32_bf16 v[78:81], v[144:147], v[232:235], v[78:81]
	v_mfma_f32_16x16x32_bf16 v[74:77], v[184:187], v[232:235], v[74:77]
	v_mfma_f32_16x16x32_bf16 v[118:121], v[188:191], v[204:207], 0
	v_mfma_f32_16x16x32_bf16 v[114:117], v[196:199], v[204:207], 0
	v_mfma_f32_16x16x32_bf16 v[102:105], v[188:191], v[212:215], 0
	v_mfma_f32_16x16x32_bf16 v[98:101], v[196:199], v[212:215], 0
	v_mfma_f32_16x16x32_bf16 v[86:89], v[188:191], v[220:223], 0
	v_mfma_f32_16x16x32_bf16 v[82:85], v[196:199], v[220:223], 0
	v_mfma_f32_16x16x32_bf16 v[70:73], v[188:191], v[228:231], 0
	v_mfma_f32_16x16x32_bf16 v[66:69], v[196:199], v[228:231], 0
	v_mfma_f32_16x16x32_bf16 v[118:121], v[192:195], v[208:211], v[118:121]
	v_mfma_f32_16x16x32_bf16 v[114:117], v[200:203], v[208:211], v[114:117]
	v_mfma_f32_16x16x32_bf16 v[102:105], v[192:195], v[216:219], v[102:105]
	v_mfma_f32_16x16x32_bf16 v[98:101], v[200:203], v[216:219], v[98:101]
	v_mfma_f32_16x16x32_bf16 v[86:89], v[192:195], v[224:227], v[86:89]
	v_mfma_f32_16x16x32_bf16 v[82:85], v[200:203], v[224:227], v[82:85]
	v_mfma_f32_16x16x32_bf16 v[70:73], v[192:195], v[232:235], v[70:73]
	v_mfma_f32_16x16x32_bf16 v[66:69], v[200:203], v[232:235], v[66:69]
	s_barrier
	s_add_i32 s35, s35, s20
	v_lshl_add_u64 v[148:149], s[66:67], 0, v[0:1]
	s_mov_b32 m0, s35
	ds_read_b128 v[204:207], v172 offset:16384
	ds_read_b128 v[208:211], v172 offset:17408
	ds_read_b128 v[212:215], v172 offset:18432
	ds_read_b128 v[216:219], v172 offset:19456
	ds_read_b128 v[220:223], v172 offset:20480
	ds_read_b128 v[224:227], v172 offset:21504
	ds_read_b128 v[228:231], v172 offset:22528
	ds_read_b128 v[232:235], v172 offset:23552
	global_load_lds_dwordx4 v[148:149], off
	s_add_i32 m0, s35, 0x2000
	v_lshl_add_u64 v[236:237], s[66:67], 0, v[134:135]
	s_add_u32 s66, s66, s16
	s_addc_u32 s67, s67, 0
	s_add_i32 s31, s31, s20
	global_load_lds_dwordx4 v[236:237], off
	v_lshl_add_u64 v[238:239], s[66:67], 0, v[0:1]
	s_mov_b32 m0, s31
	v_lshl_add_u64 v[240:241], s[66:67], 0, v[134:135]
	global_load_lds_dwordx4 v[238:239], off
	s_add_i32 m0, s31, 0x2000
	v_lshl_add_u64 v[242:243], s[10:11], 0, v[130:131]
	global_load_lds_dwordx4 v[240:241], off
	s_mov_b32 m0, s23
	v_lshl_add_u64 v[244:245], s[10:11], 0, v[132:133]
	global_load_lds_dwordx4 v[242:243], off
	s_mov_b32 m0, s52
	s_nop 0
	global_load_lds_dwordx4 v[244:245], off
	s_waitcnt vmcnt(8)
	s_waitcnt lgkmcnt(0)
	s_barrier
	s_waitcnt lgkmcnt(0)
	v_mfma_f32_16x16x32_bf16 v[62:65], v[140:143], v[204:207], 0
	v_mfma_f32_16x16x32_bf16 v[58:61], v[180:183], v[204:207], 0
	v_mfma_f32_16x16x32_bf16 v[46:49], v[140:143], v[212:215], 0
	v_mfma_f32_16x16x32_bf16 v[42:45], v[180:183], v[212:215], 0
	v_mfma_f32_16x16x32_bf16 v[30:33], v[140:143], v[220:223], 0
	v_mfma_f32_16x16x32_bf16 v[26:29], v[180:183], v[220:223], 0
	v_mfma_f32_16x16x32_bf16 v[14:17], v[140:143], v[228:231], 0
	v_mfma_f32_16x16x32_bf16 v[10:13], v[180:183], v[228:231], 0
	v_mfma_f32_16x16x32_bf16 v[62:65], v[144:147], v[208:211], v[62:65]
	v_mfma_f32_16x16x32_bf16 v[58:61], v[184:187], v[208:211], v[58:61]
	v_mfma_f32_16x16x32_bf16 v[46:49], v[144:147], v[216:219], v[46:49]
	v_mfma_f32_16x16x32_bf16 v[42:45], v[184:187], v[216:219], v[42:45]
	v_mfma_f32_16x16x32_bf16 v[30:33], v[144:147], v[224:227], v[30:33]
	v_mfma_f32_16x16x32_bf16 v[26:29], v[184:187], v[224:227], v[26:29]
	v_mfma_f32_16x16x32_bf16 v[14:17], v[144:147], v[232:235], v[14:17]
	v_mfma_f32_16x16x32_bf16 v[10:13], v[184:187], v[232:235], v[10:13]
	v_mfma_f32_16x16x32_bf16 v[54:57], v[188:191], v[204:207], 0
	v_mfma_f32_16x16x32_bf16 v[50:53], v[196:199], v[204:207], 0
	v_mfma_f32_16x16x32_bf16 v[38:41], v[188:191], v[212:215], 0
	v_mfma_f32_16x16x32_bf16 v[34:37], v[196:199], v[212:215], 0
	v_mfma_f32_16x16x32_bf16 v[22:25], v[188:191], v[220:223], 0
	v_mfma_f32_16x16x32_bf16 v[18:21], v[196:199], v[220:223], 0
	v_mfma_f32_16x16x32_bf16 v[6:9], v[188:191], v[228:231], 0
	v_mfma_f32_16x16x32_bf16 v[2:5], v[196:199], v[228:231], 0
	v_mfma_f32_16x16x32_bf16 v[54:57], v[192:195], v[208:211], v[54:57]
	v_mfma_f32_16x16x32_bf16 v[50:53], v[200:203], v[208:211], v[50:53]
	v_mfma_f32_16x16x32_bf16 v[38:41], v[192:195], v[216:219], v[38:41]
	v_mfma_f32_16x16x32_bf16 v[34:37], v[200:203], v[216:219], v[34:37]
	v_mfma_f32_16x16x32_bf16 v[22:25], v[192:195], v[224:227], v[22:25]
	v_mfma_f32_16x16x32_bf16 v[18:21], v[200:203], v[224:227], v[18:21]
	v_mfma_f32_16x16x32_bf16 v[6:9], v[192:195], v[232:235], v[6:9]
	v_mfma_f32_16x16x32_bf16 v[2:5], v[200:203], v[232:235], v[2:5]
	s_barrier
	s_add_i32 s31, 0, 0x18000
	s_add_i32 s35, 0, 0x1c000
	v_add_u32_e32 v184, s31, v160
	v_add_u32_e32 v200, s35, v160
	ds_read_b128 v[140:143], v184
	ds_read_b128 v[144:147], v184 offset:1024
	ds_read_b128 v[180:183], v184 offset:2048
	ds_read_b128 v[184:187], v184 offset:3072
	ds_read_b128 v[188:191], v200
	ds_read_b128 v[192:195], v200 offset:1024
	ds_read_b128 v[196:199], v200 offset:2048
	ds_read_b128 v[200:203], v200 offset:3072
	s_add_u32 s10, s10, s16
	s_addc_u32 s11, s11, 0
	s_mov_b32 m0, s53
	v_lshl_add_u64 v[246:247], s[10:11], 0, v[130:131]
	ds_read_b128 v[204:207], v172 offset:32768
	ds_read_b128 v[208:211], v172 offset:33792
	ds_read_b128 v[212:215], v172 offset:34816
	ds_read_b128 v[216:219], v172 offset:35840
	ds_read_b128 v[220:223], v172 offset:36864
	ds_read_b128 v[224:227], v172 offset:37888
	ds_read_b128 v[228:231], v172 offset:38912
	ds_read_b128 v[232:235], v172 offset:39936
	global_load_lds_dwordx4 v[246:247], off
	v_lshl_add_u64 v[246:247], s[10:11], 0, v[132:133]
	s_mov_b32 m0, s54
	s_nop 0
	global_load_lds_dwordx4 v[246:247], off
	s_waitcnt vmcnt(8)
	s_waitcnt lgkmcnt(0)
	s_barrier
	s_waitcnt lgkmcnt(0)
	v_mfma_f32_16x16x32_bf16 v[126:129], v[140:143], v[204:207], v[126:129]
	v_mfma_f32_16x16x32_bf16 v[122:125], v[180:183], v[204:207], v[122:125]
	v_mfma_f32_16x16x32_bf16 v[110:113], v[140:143], v[212:215], v[110:113]
	v_mfma_f32_16x16x32_bf16 v[106:109], v[180:183], v[212:215], v[106:109]
	v_mfma_f32_16x16x32_bf16 v[94:97], v[140:143], v[220:223], v[94:97]
	v_mfma_f32_16x16x32_bf16 v[90:93], v[180:183], v[220:223], v[90:93]
	v_mfma_f32_16x16x32_bf16 v[78:81], v[140:143], v[228:231], v[78:81]
	v_mfma_f32_16x16x32_bf16 v[74:77], v[180:183], v[228:231], v[74:77]
	v_mfma_f32_16x16x32_bf16 v[126:129], v[144:147], v[208:211], v[126:129]
	v_mfma_f32_16x16x32_bf16 v[122:125], v[184:187], v[208:211], v[122:125]
	v_mfma_f32_16x16x32_bf16 v[110:113], v[144:147], v[216:219], v[110:113]
	v_mfma_f32_16x16x32_bf16 v[106:109], v[184:187], v[216:219], v[106:109]
	v_mfma_f32_16x16x32_bf16 v[94:97], v[144:147], v[224:227], v[94:97]
	v_mfma_f32_16x16x32_bf16 v[90:93], v[184:187], v[224:227], v[90:93]
	v_mfma_f32_16x16x32_bf16 v[78:81], v[144:147], v[232:235], v[78:81]
	v_mfma_f32_16x16x32_bf16 v[74:77], v[184:187], v[232:235], v[74:77]
	v_mfma_f32_16x16x32_bf16 v[118:121], v[188:191], v[204:207], v[118:121]
	v_mfma_f32_16x16x32_bf16 v[114:117], v[196:199], v[204:207], v[114:117]
	v_mfma_f32_16x16x32_bf16 v[102:105], v[188:191], v[212:215], v[102:105]
	v_mfma_f32_16x16x32_bf16 v[98:101], v[196:199], v[212:215], v[98:101]
	v_mfma_f32_16x16x32_bf16 v[86:89], v[188:191], v[220:223], v[86:89]
	v_mfma_f32_16x16x32_bf16 v[82:85], v[196:199], v[220:223], v[82:85]
	v_mfma_f32_16x16x32_bf16 v[70:73], v[188:191], v[228:231], v[70:73]
	v_mfma_f32_16x16x32_bf16 v[66:69], v[196:199], v[228:231], v[66:69]
	v_mfma_f32_16x16x32_bf16 v[118:121], v[192:195], v[208:211], v[118:121]
	v_mfma_f32_16x16x32_bf16 v[114:117], v[200:203], v[208:211], v[114:117]
	v_mfma_f32_16x16x32_bf16 v[102:105], v[192:195], v[216:219], v[102:105]
	v_mfma_f32_16x16x32_bf16 v[98:101], v[200:203], v[216:219], v[98:101]
	v_mfma_f32_16x16x32_bf16 v[86:89], v[192:195], v[224:227], v[86:89]
	v_mfma_f32_16x16x32_bf16 v[82:85], v[200:203], v[224:227], v[82:85]
	v_mfma_f32_16x16x32_bf16 v[70:73], v[192:195], v[232:235], v[70:73]
	v_mfma_f32_16x16x32_bf16 v[66:69], v[200:203], v[232:235], v[66:69]
	s_barrier
	s_add_i32 s10, s31, s20
	v_lshl_add_u64 v[148:149], v[148:149], 0, s[94:95]
	s_mov_b32 m0, s10
	ds_read_b128 v[204:207], v172 offset:49152
	ds_read_b128 v[208:211], v172 offset:50176
	ds_read_b128 v[212:215], v172 offset:51200
	ds_read_b128 v[216:219], v172 offset:52224
	ds_read_b128 v[220:223], v172 offset:53248
	ds_read_b128 v[224:227], v172 offset:54272
	ds_read_b128 v[228:231], v172 offset:55296
	ds_read_b128 v[232:235], v172 offset:56320
	global_load_lds_dwordx4 v[148:149], off
	v_lshl_add_u64 v[148:149], v[236:237], 0, s[94:95]
	s_add_i32 m0, s10, 0x2000
	s_add_i32 s10, s35, s20
	global_load_lds_dwordx4 v[148:149], off
	v_lshl_add_u64 v[148:149], v[238:239], 0, s[94:95]
	s_mov_b32 m0, s10
	s_nop 0
	global_load_lds_dwordx4 v[148:149], off
	v_lshl_add_u64 v[148:149], v[240:241], 0, s[94:95]
	s_add_i32 m0, s10, 0x2000
	s_nop 0
	global_load_lds_dwordx4 v[148:149], off
	v_lshl_add_u64 v[148:149], v[242:243], 0, s[94:95]
	s_mov_b32 m0, s56
	s_nop 0
	global_load_lds_dwordx4 v[148:149], off
	v_lshl_add_u64 v[148:149], v[244:245], 0, s[94:95]
	s_mov_b32 m0, s57
	s_nop 0
	global_load_lds_dwordx4 v[148:149], off
	s_waitcnt vmcnt(8)
	s_waitcnt lgkmcnt(0)
	s_barrier
	s_waitcnt lgkmcnt(0)
	v_mfma_f32_16x16x32_bf16 v[62:65], v[140:143], v[204:207], v[62:65]
	v_mfma_f32_16x16x32_bf16 v[58:61], v[180:183], v[204:207], v[58:61]
	v_mfma_f32_16x16x32_bf16 v[46:49], v[140:143], v[212:215], v[46:49]
	v_mfma_f32_16x16x32_bf16 v[42:45], v[180:183], v[212:215], v[42:45]
	v_mfma_f32_16x16x32_bf16 v[30:33], v[140:143], v[220:223], v[30:33]
	v_mfma_f32_16x16x32_bf16 v[26:29], v[180:183], v[220:223], v[26:29]
	v_mfma_f32_16x16x32_bf16 v[14:17], v[140:143], v[228:231], v[14:17]
	v_mfma_f32_16x16x32_bf16 v[10:13], v[180:183], v[228:231], v[10:13]
	v_mfma_f32_16x16x32_bf16 v[62:65], v[144:147], v[208:211], v[62:65]
	v_mfma_f32_16x16x32_bf16 v[58:61], v[184:187], v[208:211], v[58:61]
	v_mfma_f32_16x16x32_bf16 v[46:49], v[144:147], v[216:219], v[46:49]
	v_mfma_f32_16x16x32_bf16 v[42:45], v[184:187], v[216:219], v[42:45]
	v_mfma_f32_16x16x32_bf16 v[30:33], v[144:147], v[224:227], v[30:33]
	v_mfma_f32_16x16x32_bf16 v[26:29], v[184:187], v[224:227], v[26:29]
	v_mfma_f32_16x16x32_bf16 v[14:17], v[144:147], v[232:235], v[14:17]
	v_mfma_f32_16x16x32_bf16 v[10:13], v[184:187], v[232:235], v[10:13]
	v_mfma_f32_16x16x32_bf16 v[54:57], v[188:191], v[204:207], v[54:57]
	v_mfma_f32_16x16x32_bf16 v[50:53], v[196:199], v[204:207], v[50:53]
	v_mfma_f32_16x16x32_bf16 v[38:41], v[188:191], v[212:215], v[38:41]
	v_mfma_f32_16x16x32_bf16 v[34:37], v[196:199], v[212:215], v[34:37]
	v_mfma_f32_16x16x32_bf16 v[22:25], v[188:191], v[220:223], v[22:25]
	v_mfma_f32_16x16x32_bf16 v[18:21], v[196:199], v[220:223], v[18:21]
	v_mfma_f32_16x16x32_bf16 v[6:9], v[188:191], v[228:231], v[6:9]
	v_mfma_f32_16x16x32_bf16 v[2:5], v[196:199], v[228:231], v[2:5]
	v_mfma_f32_16x16x32_bf16 v[54:57], v[192:195], v[208:211], v[54:57]
	v_mfma_f32_16x16x32_bf16 v[50:53], v[200:203], v[208:211], v[50:53]
	v_mfma_f32_16x16x32_bf16 v[38:41], v[192:195], v[216:219], v[38:41]
	v_mfma_f32_16x16x32_bf16 v[34:37], v[200:203], v[216:219], v[34:37]
	v_mfma_f32_16x16x32_bf16 v[22:25], v[192:195], v[224:227], v[22:25]
	v_mfma_f32_16x16x32_bf16 v[18:21], v[200:203], v[224:227], v[18:21]
	v_mfma_f32_16x16x32_bf16 v[6:9], v[192:195], v[232:235], v[6:9]
	v_mfma_f32_16x16x32_bf16 v[2:5], v[200:203], v[232:235], v[2:5]
	s_barrier
	s_add_u32 s2, s2, 0x100
	s_addc_u32 s3, s3, 0
	s_add_u32 s19, s19, 0x100
	s_addc_u32 s29, s29, 0
	s_cmp_ge_u32 s30, s55
	s_mov_b32 s10, s30
	s_cbranch_scc0 .LBB0_360
	s_branch .Lkexit_360

.Lkexit_360:
	s_and_b64 vcc, exec, s[14:15]
	s_cbranch_vccz .LBB0_363
	s_barrier

.LBB0_418:
	s_add_u32 s16, s16, 0x80
	s_addc_u32 s17, s17, 0
	s_add_u32 s64, s20, 0x100
	s_addc_u32 s65, s21, 0
	s_mov_b32 s20, 0
	s_add_i32 s66, s20, 2
	s_add_u32 s67, s16, 0x80
	s_addc_u32 s21, s17, 0
	s_add_i32 s72, 0, 0x10000
	s_cmp_eq_u32 s58, s20
	s_cselect_b32 s21, s1, s21
	s_cselect_b32 s20, s0, s67
	v_add_u32_e32 v140, s72, v143
	s_cselect_b32 s71, s15, s65
	s_cselect_b32 s70, s14, s64
	s_add_i32 s67, 0, 0x14000
	ds_read_b128 v[160:163], v140
	ds_read_b128 v[164:167], v140 offset:1024
	ds_read_b128 v[168:171], v140 offset:2048
	ds_read_b128 v[172:175], v140 offset:3072
	v_add_u32_e32 v140, s67, v143
	ds_read_b128 v[176:179], v140
	ds_read_b128 v[180:183], v140 offset:1024
	ds_read_b128 v[184:187], v140 offset:2048
	ds_read_b128 v[188:191], v140 offset:3072
	v_lshl_add_u64 v[140:141], s[16:17], 0, v[136:137]
	s_add_i32 m0, s35, 0xc000
	ds_read_b128 v[192:195], v146
	ds_read_b128 v[196:199], v146 offset:1024
	ds_read_b128 v[200:203], v146 offset:2048
	ds_read_b128 v[204:207], v146 offset:3072
	ds_read_b128 v[208:211], v146 offset:4096
	ds_read_b128 v[212:215], v146 offset:5120
	ds_read_b128 v[216:219], v146 offset:6144
	ds_read_b128 v[220:223], v146 offset:7168
	global_load_lds_dwordx4 v[140:141], off
	v_lshl_add_u64 v[140:141], s[16:17], 0, v[138:139]
	s_add_i32 m0, s35, 0xe000
	s_nop 0
	global_load_lds_dwordx4 v[140:141], off
	s_waitcnt vmcnt(8)
	s_waitcnt lgkmcnt(0)
	s_barrier
	s_waitcnt lgkmcnt(0)
	v_mfma_f32_16x16x32_bf16 v[126:129], v[160:163], v[192:195], 0
	v_mfma_f32_16x16x32_bf16 v[122:125], v[168:171], v[192:195], 0
	v_mfma_f32_16x16x32_bf16 v[110:113], v[160:163], v[200:203], 0
	v_mfma_f32_16x16x32_bf16 v[106:109], v[168:171], v[200:203], 0
	v_mfma_f32_16x16x32_bf16 v[94:97], v[160:163], v[208:211], 0
	v_mfma_f32_16x16x32_bf16 v[90:93], v[168:171], v[208:211], 0
	v_mfma_f32_16x16x32_bf16 v[78:81], v[160:163], v[216:219], 0
	v_mfma_f32_16x16x32_bf16 v[74:77], v[168:171], v[216:219], 0
	v_mfma_f32_16x16x32_bf16 v[126:129], v[164:167], v[196:199], v[126:129]
	v_mfma_f32_16x16x32_bf16 v[122:125], v[172:175], v[196:199], v[122:125]
	v_mfma_f32_16x16x32_bf16 v[110:113], v[164:167], v[204:207], v[110:113]
	v_mfma_f32_16x16x32_bf16 v[106:109], v[172:175], v[204:207], v[106:109]
	v_mfma_f32_16x16x32_bf16 v[94:97], v[164:167], v[212:215], v[94:97]
	v_mfma_f32_16x16x32_bf16 v[90:93], v[172:175], v[212:215], v[90:93]
	v_mfma_f32_16x16x32_bf16 v[78:81], v[164:167], v[220:223], v[78:81]
	v_mfma_f32_16x16x32_bf16 v[74:77], v[172:175], v[220:223], v[74:77]
	v_mfma_f32_16x16x32_bf16 v[118:121], v[176:179], v[192:195], 0
	v_mfma_f32_16x16x32_bf16 v[114:117], v[184:187], v[192:195], 0
	v_mfma_f32_16x16x32_bf16 v[102:105], v[176:179], v[200:203], 0
	v_mfma_f32_16x16x32_bf16 v[98:101], v[184:187], v[200:203], 0
	v_mfma_f32_16x16x32_bf16 v[86:89], v[176:179], v[208:211], 0
	v_mfma_f32_16x16x32_bf16 v[82:85], v[184:187], v[208:211], 0
	v_mfma_f32_16x16x32_bf16 v[70:73], v[176:179], v[216:219], 0
	v_mfma_f32_16x16x32_bf16 v[66:69], v[184:187], v[216:219], 0
	v_mfma_f32_16x16x32_bf16 v[118:121], v[180:183], v[196:199], v[118:121]
	v_mfma_f32_16x16x32_bf16 v[114:117], v[188:191], v[196:199], v[114:117]
	v_mfma_f32_16x16x32_bf16 v[102:105], v[180:183], v[204:207], v[102:105]
	v_mfma_f32_16x16x32_bf16 v[98:101], v[188:191], v[204:207], v[98:101]
	v_mfma_f32_16x16x32_bf16 v[86:89], v[180:183], v[212:215], v[86:89]
	v_mfma_f32_16x16x32_bf16 v[82:85], v[188:191], v[212:215], v[82:85]
	v_mfma_f32_16x16x32_bf16 v[70:73], v[180:183], v[220:223], v[70:73]
	v_mfma_f32_16x16x32_bf16 v[66:69], v[188:191], v[220:223], v[66:69]
	s_barrier
	s_add_i32 s72, s72, s30
	v_lshl_add_u64 v[140:141], s[70:71], 0, v[0:1]
	s_mov_b32 m0, s72
	ds_read_b128 v[192:195], v146 offset:16384
	ds_read_b128 v[196:199], v146 offset:17408
	ds_read_b128 v[200:203], v146 offset:18432
	ds_read_b128 v[204:207], v146 offset:19456
	ds_read_b128 v[208:211], v146 offset:20480
	ds_read_b128 v[212:215], v146 offset:21504
	ds_read_b128 v[216:219], v146 offset:22528
	ds_read_b128 v[220:223], v146 offset:23552
	global_load_lds_dwordx4 v[140:141], off
	s_add_i32 m0, s72, 0x2000
	v_lshl_add_u64 v[148:149], s[70:71], 0, v[134:135]
	s_add_u32 s70, s70, s80
	s_addc_u32 s71, s71, 0
	s_add_i32 s67, s67, s30
	global_load_lds_dwordx4 v[148:149], off
	v_lshl_add_u64 v[224:225], s[70:71], 0, v[0:1]
	s_mov_b32 m0, s67
	v_lshl_add_u64 v[226:227], s[70:71], 0, v[134:135]
	global_load_lds_dwordx4 v[224:225], off
	s_add_i32 m0, s67, 0x2000
	v_lshl_add_u64 v[228:229], s[20:21], 0, v[130:131]
	global_load_lds_dwordx4 v[226:227], off
	s_mov_b32 m0, s35
	v_lshl_add_u64 v[230:231], s[20:21], 0, v[132:133]
	global_load_lds_dwordx4 v[228:229], off
	s_mov_b32 m0, s52
	s_nop 0
	global_load_lds_dwordx4 v[230:231], off
	s_waitcnt vmcnt(8)
	s_waitcnt lgkmcnt(0)
	s_barrier
	s_waitcnt lgkmcnt(0)
	v_mfma_f32_16x16x32_bf16 v[62:65], v[160:163], v[192:195], 0
	v_mfma_f32_16x16x32_bf16 v[58:61], v[168:171], v[192:195], 0
	v_mfma_f32_16x16x32_bf16 v[46:49], v[160:163], v[200:203], 0
	v_mfma_f32_16x16x32_bf16 v[42:45], v[168:171], v[200:203], 0
	v_mfma_f32_16x16x32_bf16 v[30:33], v[160:163], v[208:211], 0
	v_mfma_f32_16x16x32_bf16 v[26:29], v[168:171], v[208:211], 0
	v_mfma_f32_16x16x32_bf16 v[14:17], v[160:163], v[216:219], 0
	v_mfma_f32_16x16x32_bf16 v[10:13], v[168:171], v[216:219], 0
	v_mfma_f32_16x16x32_bf16 v[62:65], v[164:167], v[196:199], v[62:65]
	v_mfma_f32_16x16x32_bf16 v[58:61], v[172:175], v[196:199], v[58:61]
	v_mfma_f32_16x16x32_bf16 v[46:49], v[164:167], v[204:207], v[46:49]
	v_mfma_f32_16x16x32_bf16 v[42:45], v[172:175], v[204:207], v[42:45]
	v_mfma_f32_16x16x32_bf16 v[30:33], v[164:167], v[212:215], v[30:33]
	v_mfma_f32_16x16x32_bf16 v[26:29], v[172:175], v[212:215], v[26:29]
	v_mfma_f32_16x16x32_bf16 v[14:17], v[164:167], v[220:223], v[14:17]
	v_mfma_f32_16x16x32_bf16 v[10:13], v[172:175], v[220:223], v[10:13]
	v_mfma_f32_16x16x32_bf16 v[54:57], v[176:179], v[192:195], 0
	v_mfma_f32_16x16x32_bf16 v[50:53], v[184:187], v[192:195], 0
	v_mfma_f32_16x16x32_bf16 v[38:41], v[176:179], v[200:203], 0
	v_mfma_f32_16x16x32_bf16 v[34:37], v[184:187], v[200:203], 0
	v_mfma_f32_16x16x32_bf16 v[22:25], v[176:179], v[208:211], 0
	v_mfma_f32_16x16x32_bf16 v[18:21], v[184:187], v[208:211], 0
	v_mfma_f32_16x16x32_bf16 v[6:9], v[176:179], v[216:219], 0
	v_mfma_f32_16x16x32_bf16 v[2:5], v[184:187], v[216:219], 0
	v_mfma_f32_16x16x32_bf16 v[54:57], v[180:183], v[196:199], v[54:57]
	v_mfma_f32_16x16x32_bf16 v[50:53], v[188:191], v[196:199], v[50:53]
	v_mfma_f32_16x16x32_bf16 v[38:41], v[180:183], v[204:207], v[38:41]
	v_mfma_f32_16x16x32_bf16 v[34:37], v[188:191], v[204:207], v[34:37]
	v_mfma_f32_16x16x32_bf16 v[22:25], v[180:183], v[212:215], v[22:25]
	v_mfma_f32_16x16x32_bf16 v[18:21], v[188:191], v[212:215], v[18:21]
	v_mfma_f32_16x16x32_bf16 v[6:9], v[180:183], v[220:223], v[6:9]
	v_mfma_f32_16x16x32_bf16 v[2:5], v[188:191], v[220:223], v[2:5]
	s_barrier
	s_add_i32 s67, 0, 0x18000
	v_add_u32_e32 v159, s67, v143
	s_add_i32 s70, 0, 0x1c000
	ds_read_b128 v[160:163], v159
	ds_read_b128 v[164:167], v159 offset:1024
	ds_read_b128 v[168:171], v159 offset:2048
	ds_read_b128 v[172:175], v159 offset:3072
	v_add_u32_e32 v159, s70, v143
	ds_read_b128 v[176:179], v159
	ds_read_b128 v[180:183], v159 offset:1024
	ds_read_b128 v[184:187], v159 offset:2048
	ds_read_b128 v[188:191], v159 offset:3072
	s_add_u32 s20, s20, s80
	s_addc_u32 s21, s21, 0
	s_mov_b32 m0, s53
	v_lshl_add_u64 v[232:233], s[20:21], 0, v[130:131]
	ds_read_b128 v[192:195], v146 offset:32768
	ds_read_b128 v[196:199], v146 offset:33792
	ds_read_b128 v[200:203], v146 offset:34816
	ds_read_b128 v[204:207], v146 offset:35840
	ds_read_b128 v[208:211], v146 offset:36864
	ds_read_b128 v[212:215], v146 offset:37888
	ds_read_b128 v[216:219], v146 offset:38912
	ds_read_b128 v[220:223], v146 offset:39936
	global_load_lds_dwordx4 v[232:233], off
	v_lshl_add_u64 v[232:233], s[20:21], 0, v[132:133]
	s_mov_b32 m0, s54
	s_nop 0
	global_load_lds_dwordx4 v[232:233], off
	s_waitcnt vmcnt(8)
	s_waitcnt lgkmcnt(0)
	s_barrier
	s_waitcnt lgkmcnt(0)
	v_mfma_f32_16x16x32_bf16 v[126:129], v[160:163], v[192:195], v[126:129]
	v_mfma_f32_16x16x32_bf16 v[122:125], v[168:171], v[192:195], v[122:125]
	v_mfma_f32_16x16x32_bf16 v[110:113], v[160:163], v[200:203], v[110:113]
	v_mfma_f32_16x16x32_bf16 v[106:109], v[168:171], v[200:203], v[106:109]
	v_mfma_f32_16x16x32_bf16 v[94:97], v[160:163], v[208:211], v[94:97]
	v_mfma_f32_16x16x32_bf16 v[90:93], v[168:171], v[208:211], v[90:93]
	v_mfma_f32_16x16x32_bf16 v[78:81], v[160:163], v[216:219], v[78:81]
	v_mfma_f32_16x16x32_bf16 v[74:77], v[168:171], v[216:219], v[74:77]
	v_mfma_f32_16x16x32_bf16 v[126:129], v[164:167], v[196:199], v[126:129]
	v_mfma_f32_16x16x32_bf16 v[122:125], v[172:175], v[196:199], v[122:125]
	v_mfma_f32_16x16x32_bf16 v[110:113], v[164:167], v[204:207], v[110:113]
	v_mfma_f32_16x16x32_bf16 v[106:109], v[172:175], v[204:207], v[106:109]
	v_mfma_f32_16x16x32_bf16 v[94:97], v[164:167], v[212:215], v[94:97]
	v_mfma_f32_16x16x32_bf16 v[90:93], v[172:175], v[212:215], v[90:93]
	v_mfma_f32_16x16x32_bf16 v[78:81], v[164:167], v[220:223], v[78:81]
	v_mfma_f32_16x16x32_bf16 v[74:77], v[172:175], v[220:223], v[74:77]
	v_mfma_f32_16x16x32_bf16 v[118:121], v[176:179], v[192:195], v[118:121]
	v_mfma_f32_16x16x32_bf16 v[114:117], v[184:187], v[192:195], v[114:117]
	v_mfma_f32_16x16x32_bf16 v[102:105], v[176:179], v[200:203], v[102:105]
	v_mfma_f32_16x16x32_bf16 v[98:101], v[184:187], v[200:203], v[98:101]
	v_mfma_f32_16x16x32_bf16 v[86:89], v[176:179], v[208:211], v[86:89]
	v_mfma_f32_16x16x32_bf16 v[82:85], v[184:187], v[208:211], v[82:85]
	v_mfma_f32_16x16x32_bf16 v[70:73], v[176:179], v[216:219], v[70:73]
	v_mfma_f32_16x16x32_bf16 v[66:69], v[184:187], v[216:219], v[66:69]
	v_mfma_f32_16x16x32_bf16 v[118:121], v[180:183], v[196:199], v[118:121]
	v_mfma_f32_16x16x32_bf16 v[114:117], v[188:191], v[196:199], v[114:117]
	v_mfma_f32_16x16x32_bf16 v[102:105], v[180:183], v[204:207], v[102:105]
	v_mfma_f32_16x16x32_bf16 v[98:101], v[188:191], v[204:207], v[98:101]
	v_mfma_f32_16x16x32_bf16 v[86:89], v[180:183], v[212:215], v[86:89]
	v_mfma_f32_16x16x32_bf16 v[82:85], v[188:191], v[212:215], v[82:85]
	v_mfma_f32_16x16x32_bf16 v[70:73], v[180:183], v[220:223], v[70:73]
	v_mfma_f32_16x16x32_bf16 v[66:69], v[188:191], v[220:223], v[66:69]
	s_barrier
	s_add_i32 s20, s67, s30
	v_lshl_add_u64 v[140:141], v[140:141], 0, s[94:95]
	s_mov_b32 m0, s20
	ds_read_b128 v[192:195], v146 offset:49152
	ds_read_b128 v[196:199], v146 offset:50176
	ds_read_b128 v[200:203], v146 offset:51200
	ds_read_b128 v[204:207], v146 offset:52224
	ds_read_b128 v[208:211], v146 offset:53248
	ds_read_b128 v[212:215], v146 offset:54272
	ds_read_b128 v[216:219], v146 offset:55296
	ds_read_b128 v[220:223], v146 offset:56320
	global_load_lds_dwordx4 v[140:141], off
	v_lshl_add_u64 v[140:141], v[148:149], 0, s[94:95]
	s_add_i32 m0, s20, 0x2000
	s_add_i32 s20, s70, s30
	global_load_lds_dwordx4 v[140:141], off
	v_lshl_add_u64 v[140:141], v[224:225], 0, s[94:95]
	s_mov_b32 m0, s20
	s_nop 0
	global_load_lds_dwordx4 v[140:141], off
	v_lshl_add_u64 v[140:141], v[226:227], 0, s[94:95]
	s_add_i32 m0, s20, 0x2000
	s_nop 0
	global_load_lds_dwordx4 v[140:141], off
	v_lshl_add_u64 v[140:141], v[228:229], 0, s[94:95]
	s_mov_b32 m0, s55
	s_nop 0
	global_load_lds_dwordx4 v[140:141], off
	v_lshl_add_u64 v[140:141], v[230:231], 0, s[94:95]
	s_mov_b32 m0, s56
	s_nop 0
	global_load_lds_dwordx4 v[140:141], off
	s_waitcnt vmcnt(8)
	s_waitcnt lgkmcnt(0)
	s_barrier
	s_waitcnt lgkmcnt(0)
	v_mfma_f32_16x16x32_bf16 v[62:65], v[160:163], v[192:195], v[62:65]
	v_mfma_f32_16x16x32_bf16 v[58:61], v[168:171], v[192:195], v[58:61]
	v_mfma_f32_16x16x32_bf16 v[46:49], v[160:163], v[200:203], v[46:49]
	v_mfma_f32_16x16x32_bf16 v[42:45], v[168:171], v[200:203], v[42:45]
	v_mfma_f32_16x16x32_bf16 v[30:33], v[160:163], v[208:211], v[30:33]
	v_mfma_f32_16x16x32_bf16 v[26:29], v[168:171], v[208:211], v[26:29]
	v_mfma_f32_16x16x32_bf16 v[14:17], v[160:163], v[216:219], v[14:17]
	v_mfma_f32_16x16x32_bf16 v[10:13], v[168:171], v[216:219], v[10:13]
	v_mfma_f32_16x16x32_bf16 v[62:65], v[164:167], v[196:199], v[62:65]
	v_mfma_f32_16x16x32_bf16 v[58:61], v[172:175], v[196:199], v[58:61]
	v_mfma_f32_16x16x32_bf16 v[46:49], v[164:167], v[204:207], v[46:49]
	v_mfma_f32_16x16x32_bf16 v[42:45], v[172:175], v[204:207], v[42:45]
	v_mfma_f32_16x16x32_bf16 v[30:33], v[164:167], v[212:215], v[30:33]
	v_mfma_f32_16x16x32_bf16 v[26:29], v[172:175], v[212:215], v[26:29]
	v_mfma_f32_16x16x32_bf16 v[14:17], v[164:167], v[220:223], v[14:17]
	v_mfma_f32_16x16x32_bf16 v[10:13], v[172:175], v[220:223], v[10:13]
	v_mfma_f32_16x16x32_bf16 v[54:57], v[176:179], v[192:195], v[54:57]
	v_mfma_f32_16x16x32_bf16 v[50:53], v[184:187], v[192:195], v[50:53]
	v_mfma_f32_16x16x32_bf16 v[38:41], v[176:179], v[200:203], v[38:41]
	v_mfma_f32_16x16x32_bf16 v[34:37], v[184:187], v[200:203], v[34:37]
	v_mfma_f32_16x16x32_bf16 v[22:25], v[176:179], v[208:211], v[22:25]
	v_mfma_f32_16x16x32_bf16 v[18:21], v[184:187], v[208:211], v[18:21]
	v_mfma_f32_16x16x32_bf16 v[6:9], v[176:179], v[216:219], v[6:9]
	v_mfma_f32_16x16x32_bf16 v[2:5], v[184:187], v[216:219], v[2:5]
	v_mfma_f32_16x16x32_bf16 v[54:57], v[180:183], v[196:199], v[54:57]
	v_mfma_f32_16x16x32_bf16 v[50:53], v[188:191], v[196:199], v[50:53]
	v_mfma_f32_16x16x32_bf16 v[38:41], v[180:183], v[204:207], v[38:41]
	v_mfma_f32_16x16x32_bf16 v[34:37], v[188:191], v[204:207], v[34:37]
	v_mfma_f32_16x16x32_bf16 v[22:25], v[180:183], v[212:215], v[22:25]
	v_mfma_f32_16x16x32_bf16 v[18:21], v[188:191], v[212:215], v[18:21]
	v_mfma_f32_16x16x32_bf16 v[6:9], v[180:183], v[220:223], v[6:9]
	v_mfma_f32_16x16x32_bf16 v[2:5], v[188:191], v[220:223], v[2:5]
	s_barrier
	s_add_u32 s16, s16, 0x100
	s_addc_u32 s17, s17, 0
	s_add_u32 s64, s64, 0x100
	s_addc_u32 s65, s65, 0
	s_cmp_ge_u32 s66, s57
	s_mov_b32 s20, s66
	s_cbranch_scc0 .LBB0_419
	s_branch .Lkexit_419
